# same as previous best but without the phase-entry stagger in the FFN-up phases
# speedup vs baseline: 1.0137x; 1.0056x over previous
.LBB0_939:
	s_or_b64 exec, exec, s[38:39]
	s_cmpk_gt_i32 s2, 0x5ff
	s_waitcnt lgkmcnt(0)
	s_barrier
	s_cbranch_scc1 .LBB0_944
	s_mov_b32 s101, 0
	s_add_i32 s3, 0, 0x240a8
	v_mov_b32_e32 v133, s3
	s_mov_b64 s[4:5], 0x2400000
	s_mov_b64 s[6:7], 0x1200000
	s_mov_b32 s20, 0x3ffff0
	v_mov_b32_e32 v129, 0
	s_mov_b32 s21, 0xc000
	s_movk_i32 s22, 0xc000
	s_movk_i32 s23, 0x1800
	s_mov_b64 s[8:9], 0x1200080
	s_mov_b64 s[10:11], 0x2400080
	s_add_i32 s24, 0, 0x10000
	s_mov_b32 s25, 0x18000
	s_add_i32 s26, 0, 0x18000
	s_movk_i32 s27, 0x2400
	s_mov_b64 s[12:13], 0x11400000
	s_mov_b32 s28, 0x24000
	s_mov_b32 s29, 0x60000
	s_mov_b32 s30, 0x6c000
	s_mov_b32 s31, 0x78000
	s_mov_b32 s34, 0x84000
	s_mov_b32 s35, 0x90000
	s_mov_b32 s38, 0x9c000
	s_mov_b32 s39, s2

.LBB0_1037:
	s_or_b64 exec, exec, s[38:39]
	s_cmpk_gt_i32 s2, 0x4ff
	s_waitcnt lgkmcnt(0)
	s_barrier
	s_cbranch_scc1 .LBB0_1042
	s_mov_b32 s101, 0
	s_add_i32 s20, 0, 0x240a8
	s_movk_i32 s3, 0x600
	v_mov_b32_e32 v133, s20
	s_mov_b64 s[4:5], 0x2400000
	s_mov_b64 s[6:7], 0x1200000
	s_mov_b32 s21, 0x3ffff0
	v_mov_b32_e32 v129, 0
	s_mov_b32 s22, 0xa000
	s_movk_i32 s23, 0xc000
	s_mov_b64 s[8:9], 0x1200080
	s_mov_b64 s[10:11], 0x2400080
	s_add_i32 s24, 0, 0x10000
	s_add_i32 s25, 0, 0x18000
	s_movk_i32 s26, 0x1400
	s_movk_i32 s27, 0x2400
	s_mov_b64 s[12:13], 0x11400000
	s_mov_b32 s28, 0x14000
	s_mov_b32 s29, 0x1e000
	s_mov_b32 s30, 0x50000
	s_mov_b32 s31, 0x5a000
	s_mov_b32 s34, 0x64000
	s_mov_b32 s35, 0x6e000
	s_mov_b32 s38, 0x78000
	s_mov_b32 s39, 0x82000
	s_mov_b32 s42, s2
